# barriers after phases whose stores are all write-through no longer issue the L2 write-back
# speedup vs baseline: 1.0178x; 1.0028x over previous
; __device__ __forceinline__ unsigned xb_ld(unsigned* p)              { return __hip_atomic_load(p, __ATOMIC_RELAXED, __HIP_MEMORY_SCOPE_AGENT); }
; __device__ __forceinline__ unsigned xb_add(unsigned* p, unsigned v) { return __hip_atomic_fetch_add(p, v, __ATOMIC_RELAXED, __HIP_MEMORY_SCOPE_AGENT); }
; #define XB_SPIN(cond, bar) do { unsigned _sp = 0; while (cond) { __builtin_amdgcn_s_sleep(1); \
;     if ((++_sp & 255u) == 0u) { if (xb_ld(&(bar)[XB_TMO])) break; if (_sp > XB_SPIN_CAP) { atomicAdd(&(bar)[XB_TMO], 1u); break; } } } } while (0)
; __device__ __forceinline__ void xcd_barrier(const XcdBarrier& b) {
;     ...
;         unsigned nloc = b.st[0], nx = b.st[1];
;         if (nloc == 0u) { xcd_barrier_complete(bar, b.x, nloc, nx); b.st[0] = nloc; b.st[1] = nx; }
;         const unsigned old = xb_add(&bar[XB_XSUB(b.x)], 1u);
;         const unsigned gen = old / nloc;
;         if (old + 1u == (gen + 1u) * nloc) {
;             __builtin_amdgcn_fence(__ATOMIC_RELEASE, "agent");
;             asm volatile("s_waitcnt vmcnt(0)" ::: "memory");
;             const unsigned og = xb_add(&bar[XB_TOP], 1u);
;             const unsigned tg = og / nx;
;             if (og + 1u == (tg + 1u) * nx) xb_add(&bar[XB_TOPGEN], 1u);
;             else XB_SPIN(xb_ld(&bar[XB_TOPGEN]) == tg, bar);
;             __builtin_amdgcn_fence(__ATOMIC_ACQUIRE, "agent");
;             xb_add(&bar[XB_XGEN(b.x)], 1u);
;             asm volatile("s_waitcnt vmcnt(0)" ::: "memory");
.LBB0_94:
	s_waitcnt lgkmcnt(0)
	v_readlane_b32 s15, v246, 3
	v_readlane_b32 s8, v246, 1
	v_readlane_b32 s9, v246, 2
	v_mov_b32_e32 v3, 0x1400
	v_mov_b32_e32 v4, 1
	s_lshl_b32 s15, s15, 8
	s_add_u32 s38, s8, s15
	s_addc_u32 s39, s9, 0
	s_add_u32 s40, s8, 0x200
	s_addc_u32 s41, s9, 0
	v_cvt_f32_u32_e32 v6, v2
	v_sub_u32_e32 v7, 0, v2
	global_atomic_add v5, v3, v4, s[38:39] sc0
	v_rcp_iflag_f32_e32 v6, v6
	v_mov_b32_e32 v10, 0
	v_mul_f32_e32 v6, 0x4f7ffffe, v6
	v_cvt_u32_f32_e32 v6, v6
	v_mul_lo_u32 v7, v7, v6
	v_mul_hi_u32 v7, v6, v7
	v_add_u32_e32 v6, v6, v7
	s_waitcnt vmcnt(0)
	v_mul_hi_u32 v1, v5, v6
	v_mul_lo_u32 v7, v1, v2
	v_sub_u32_e32 v7, v5, v7
	v_add_u32_e32 v8, 1, v1
	v_cmp_ge_u32_e32 vcc, v7, v2
	s_nop 1
	v_cndmask_b32_e32 v1, v1, v8, vcc
	v_sub_u32_e32 v8, v7, v2
	v_cndmask_b32_e32 v7, v7, v8, vcc
	v_add_u32_e32 v8, 1, v1
	v_cmp_ge_u32_e32 vcc, v7, v2
	v_add_u32_e32 v9, 1, v5
	s_nop 0
	v_cndmask_b32_e32 v1, v1, v8, vcc
	v_add_u32_e32 v8, 1, v1
	v_mul_lo_u32 v7, v8, v2
	v_cmp_ne_u32_e32 vcc, v9, v7
	s_cbranch_vccnz .Lxb_wait_0
	buffer_wbl2 sc1
	s_waitcnt vmcnt(0)
	v_mov_b32_e32 v3, 0x3400
	global_atomic_add v5, v3, v4, s[8:9] sc0
	v_mul_lo_u32 v7, v8, v0
	s_waitcnt vmcnt(0)
	v_add_u32_e32 v9, 1, v5
	v_cmp_ne_u32_e32 vcc, v9, v7
	s_cbranch_vccnz .Lxb_wait_0
	v_mov_b32_e32 v3, 0x2400
	global_atomic_add v3, v4, s[8:9]
	v_mov_b32_e32 v3, 0x2500
	global_atomic_add v3, v4, s[8:9]
	v_mov_b32_e32 v3, 0x2600
	global_atomic_add v3, v4, s[8:9]
	v_mov_b32_e32 v3, 0x2700
	global_atomic_add v3, v4, s[8:9]
	v_mov_b32_e32 v3, 0x2800
	global_atomic_add v3, v4, s[8:9]
	v_mov_b32_e32 v3, 0x2900
	global_atomic_add v3, v4, s[8:9]
	v_mov_b32_e32 v3, 0x2a00
	global_atomic_add v3, v4, s[8:9]
	v_mov_b32_e32 v3, 0x2b00
	global_atomic_add v3, v4, s[8:9]
	v_mov_b32_e32 v3, 0x2c00
	global_atomic_add v3, v4, s[8:9]
	v_mov_b32_e32 v3, 0x2d00
	global_atomic_add v3, v4, s[8:9]
	v_mov_b32_e32 v3, 0x2e00
	global_atomic_add v3, v4, s[8:9]
	v_mov_b32_e32 v3, 0x2f00
	global_atomic_add v3, v4, s[8:9]
	v_mov_b32_e32 v3, 0x3000
	global_atomic_add v3, v4, s[8:9]
	v_mov_b32_e32 v3, 0x3100
	global_atomic_add v3, v4, s[8:9]
	v_mov_b32_e32 v3, 0x3200
	global_atomic_add v3, v4, s[8:9]
	v_mov_b32_e32 v3, 0x3300
	global_atomic_add v3, v4, s[8:9]
	s_branch .Lxb_out_0

; __device__ __forceinline__ unsigned xb_ld(unsigned* p)              { return __hip_atomic_load(p, __ATOMIC_RELAXED, __HIP_MEMORY_SCOPE_AGENT); }
; __device__ __forceinline__ unsigned xb_add(unsigned* p, unsigned v) { return __hip_atomic_fetch_add(p, v, __ATOMIC_RELAXED, __HIP_MEMORY_SCOPE_AGENT); }
; #define XB_SPIN(cond, bar) do { unsigned _sp = 0; while (cond) { __builtin_amdgcn_s_sleep(1); \
;     if ((++_sp & 255u) == 0u) { if (xb_ld(&(bar)[XB_TMO])) break; if (_sp > XB_SPIN_CAP) { atomicAdd(&(bar)[XB_TMO], 1u); break; } } } } while (0)
; __device__ __forceinline__ void xcd_barrier(const XcdBarrier& b) {
;     ...
;         unsigned nloc = b.st[0], nx = b.st[1];
;         if (nloc == 0u) { xcd_barrier_complete(bar, b.x, nloc, nx); b.st[0] = nloc; b.st[1] = nx; }
;         const unsigned old = xb_add(&bar[XB_XSUB(b.x)], 1u);
;         const unsigned gen = old / nloc;
;         if (old + 1u == (gen + 1u) * nloc) {
;             __builtin_amdgcn_fence(__ATOMIC_RELEASE, "agent");
;             asm volatile("s_waitcnt vmcnt(0)" ::: "memory");
;             const unsigned og = xb_add(&bar[XB_TOP], 1u);
;             const unsigned tg = og / nx;
;             if (og + 1u == (tg + 1u) * nx) xb_add(&bar[XB_TOPGEN], 1u);
;             else XB_SPIN(xb_ld(&bar[XB_TOPGEN]) == tg, bar);
;             __builtin_amdgcn_fence(__ATOMIC_ACQUIRE, "agent");
;             xb_add(&bar[XB_XGEN(b.x)], 1u);
;             asm volatile("s_waitcnt vmcnt(0)" ::: "memory");
.LBB0_165:
	s_waitcnt lgkmcnt(0)
	v_readlane_b32 s15, v246, 3
	v_readlane_b32 s8, v246, 1
	v_readlane_b32 s9, v246, 2
	v_mov_b32_e32 v3, 0x1400
	v_mov_b32_e32 v4, 1
	s_lshl_b32 s15, s15, 8
	s_add_u32 s38, s8, s15
	s_addc_u32 s39, s9, 0
	s_add_u32 s40, s8, 0x200
	s_addc_u32 s41, s9, 0
	v_cvt_f32_u32_e32 v6, v2
	v_sub_u32_e32 v7, 0, v2
	global_atomic_add v5, v3, v4, s[38:39] sc0
	v_rcp_iflag_f32_e32 v6, v6
	v_mov_b32_e32 v10, 0
	v_mul_f32_e32 v6, 0x4f7ffffe, v6
	v_cvt_u32_f32_e32 v6, v6
	v_mul_lo_u32 v7, v7, v6
	v_mul_hi_u32 v7, v6, v7
	v_add_u32_e32 v6, v6, v7
	s_waitcnt vmcnt(0)
	v_mul_hi_u32 v1, v5, v6
	v_mul_lo_u32 v7, v1, v2
	v_sub_u32_e32 v7, v5, v7
	v_add_u32_e32 v8, 1, v1
	v_cmp_ge_u32_e32 vcc, v7, v2
	s_nop 1
	v_cndmask_b32_e32 v1, v1, v8, vcc
	v_sub_u32_e32 v8, v7, v2
	v_cndmask_b32_e32 v7, v7, v8, vcc
	v_add_u32_e32 v8, 1, v1
	v_cmp_ge_u32_e32 vcc, v7, v2
	v_add_u32_e32 v9, 1, v5
	s_nop 0
	v_cndmask_b32_e32 v1, v1, v8, vcc
	v_add_u32_e32 v8, 1, v1
	v_mul_lo_u32 v7, v8, v2
	v_cmp_ne_u32_e32 vcc, v9, v7
	s_cbranch_vccnz .Lxb_wait_1
	v_mov_b32_e32 v3, 0x3400
	global_atomic_add v5, v3, v4, s[8:9] sc0
	v_mul_lo_u32 v7, v8, v0
	s_waitcnt vmcnt(0)
	v_add_u32_e32 v9, 1, v5
	v_cmp_ne_u32_e32 vcc, v9, v7
	s_cbranch_vccnz .Lxb_wait_1
	v_mov_b32_e32 v3, 0x2400
	global_atomic_add v3, v4, s[8:9]
	v_mov_b32_e32 v3, 0x2500
	global_atomic_add v3, v4, s[8:9]
	v_mov_b32_e32 v3, 0x2600
	global_atomic_add v3, v4, s[8:9]
	v_mov_b32_e32 v3, 0x2700
	global_atomic_add v3, v4, s[8:9]
	v_mov_b32_e32 v3, 0x2800
	global_atomic_add v3, v4, s[8:9]
	v_mov_b32_e32 v3, 0x2900
	global_atomic_add v3, v4, s[8:9]
	v_mov_b32_e32 v3, 0x2a00
	global_atomic_add v3, v4, s[8:9]
	v_mov_b32_e32 v3, 0x2b00
	global_atomic_add v3, v4, s[8:9]
	v_mov_b32_e32 v3, 0x2c00
	global_atomic_add v3, v4, s[8:9]
	v_mov_b32_e32 v3, 0x2d00
	global_atomic_add v3, v4, s[8:9]
	v_mov_b32_e32 v3, 0x2e00
	global_atomic_add v3, v4, s[8:9]
	v_mov_b32_e32 v3, 0x2f00
	global_atomic_add v3, v4, s[8:9]
	v_mov_b32_e32 v3, 0x3000
	global_atomic_add v3, v4, s[8:9]
	v_mov_b32_e32 v3, 0x3100
	global_atomic_add v3, v4, s[8:9]
	v_mov_b32_e32 v3, 0x3200
	global_atomic_add v3, v4, s[8:9]
	v_mov_b32_e32 v3, 0x3300
	global_atomic_add v3, v4, s[8:9]
	s_branch .Lxb_out_1
